# P15 carry-prefix loop: 8 loads of each unrolled step issued together with counted vmcnt (was 3 serialized round trips)
# speedup vs baseline: 1.0748x; 1.0074x over previous
; __global__ void __launch_bounds__(512, 2) fwd_kernel(Params p) {
;     ...
;             if (tid < LRU_W / 4) { const int c = tid * 4; float h[4] = {0.f, 0.f, 0.f, 0.f};
; #pragma unroll 4
;                 for (int j = 0; j < ch; ++j) { const size_t ci = ((size_t)b * NCHUNK + j) * LRU_W + c; const f32x4 cp = *(const f32x4*)(carryP + ci), chh = *(const f32x4*)(carryH + ci);
;                     h[0] = cp.x * h[0] + chh.x; h[1] = cp.y * h[1] + chh.y; h[2] = cp.z * h[2] + chh.z; h[3] = cp.w * h[3] + chh.w; }
.LBB0_1504:
	v_add_co_u32_e32 v76, vcc, 0xffe7c000, v74
	s_add_i32 s39, s39, 4
	s_nop 0
	v_addc_co_u32_e32 v77, vcc, -1, v75, vcc
	v_add_co_u32_e32 v84, vcc, 0xffffc000, v74
	s_nop 1
	v_addc_co_u32_e32 v85, vcc, -1, v75, vcc
	v_add_co_u32_e32 v88, vcc, 0xffe7d000, v74
	global_load_dwordx4 v[80:83], v[76:77], off offset:-2048
	s_nop 0
	global_load_dwordx4 v[84:87], v[84:85], off offset:-2048
	v_addc_co_u32_e32 v89, vcc, -1, v75, vcc
	v_add_co_u32_e32 v76, vcc, 0xffffd000, v74
	s_nop 1
	v_addc_co_u32_e32 v77, vcc, -1, v75, vcc
	v_add_co_u32_e32 v96, vcc, 0xffe7f000, v74
	global_load_dwordx4 v[88:91], v[88:89], off
	s_nop 0
	global_load_dwordx4 v[92:95], v[76:77], off
	v_addc_co_u32_e32 v97, vcc, -1, v75, vcc
	v_add_co_u32_e32 v76, vcc, 0xfffff000, v74
	s_nop 1
	v_addc_co_u32_e32 v77, vcc, -1, v75, vcc
	v_add_co_u32_e32 v104, vcc, 0xffe80000, v74
	global_load_dwordx4 v[96:99], v[96:97], off offset:-2048
	s_nop 0
	global_load_dwordx4 v[100:103], v[76:77], off offset:-2048
	v_addc_co_u32_e32 v105, vcc, -1, v75, vcc
	global_load_dwordx4 v[104:107], v[104:105], off
	s_nop 0
	global_load_dwordx4 v[108:111], v[74:75], off
	s_cmp_eq_u32 s38, s39
	v_lshl_add_u64 v[74:75], v[74:75], 0, s[20:21]
	s_waitcnt vmcnt(6)
	v_pk_fma_f32 v[72:73], v[72:73], v[80:81], v[84:85]
	v_pk_fma_f32 v[76:77], v[78:79], v[82:83], v[86:87]
	s_waitcnt vmcnt(4)
	v_pk_fma_f32 v[72:73], v[72:73], v[88:89], v[92:93]
	v_pk_fma_f32 v[76:77], v[76:77], v[90:91], v[94:95]
	s_waitcnt vmcnt(2)
	v_pk_fma_f32 v[72:73], v[72:73], v[96:97], v[100:101]
	v_pk_fma_f32 v[76:77], v[76:77], v[98:99], v[102:103]
	s_waitcnt vmcnt(0)
	v_pk_fma_f32 v[72:73], v[72:73], v[104:105], v[108:109]
	v_pk_fma_f32 v[78:79], v[76:77], v[106:107], v[110:111]
	s_cbranch_scc0 .LBB0_1504
	s_and_b32 s39, s46, 3
	s_cmp_eq_u32 s39, 0
	s_cbranch_scc0 .LBB0_1508
	s_branch .LBB0_1510
